# UP epilogue: conv FMAs of the four row groups interleaved (dependent packed FMAs four issue slots apart)
# baseline (speedup 1.0000x reference)
.Lnepia_j1:
	v_mov_b32_dpp v118, v78 row_shr:1 row_mask:0xf bank_mask:0xf
	v_mov_b32_dpp v122, v138 row_shr:1 row_mask:0xf bank_mask:0xf
	v_mov_b32_dpp v119, v79 row_shr:1 row_mask:0xf bank_mask:0xf
	v_mov_b32_dpp v123, v139 row_shr:1 row_mask:0xf bank_mask:0xf
	v_mov_b32_dpp v120, v80 row_shr:1 row_mask:0xf bank_mask:0xf
	v_mov_b32_dpp v124, v140 row_shr:1 row_mask:0xf bank_mask:0xf
	v_mov_b32_dpp v121, v81 row_shr:1 row_mask:0xf bank_mask:0xf
	v_mov_b32_dpp v125, v141 row_shr:1 row_mask:0xf bank_mask:0xf
	v_pk_fma_f32 v[138:139], v[202:203], v[138:139], v[206:207]
	v_pk_fma_f32 v[140:141], v[204:205], v[140:141], v[208:209]
	v_pk_fma_f32 v[138:139], v[198:199], v[78:79], v[138:139]
	v_pk_fma_f32 v[140:141], v[200:201], v[80:81], v[140:141]
	v_pk_fma_f32 v[78:79], v[202:203], v[78:79], v[206:207]
	v_pk_fma_f32 v[80:81], v[204:205], v[80:81], v[208:209]
	v_pk_fma_f32 v[138:139], v[194:195], v[130:131], v[138:139]
	v_pk_fma_f32 v[140:141], v[196:197], v[132:133], v[140:141]
	v_pk_fma_f32 v[78:79], v[198:199], v[130:131], v[78:79]
	v_pk_fma_f32 v[80:81], v[200:201], v[132:133], v[80:81]
	v_pk_fma_f32 v[130:131], v[202:203], v[130:131], v[206:207]
	v_pk_fma_f32 v[132:133], v[204:205], v[132:133], v[208:209]
	v_pk_fma_f32 v[78:79], v[194:195], v[134:135], v[78:79]
	v_pk_fma_f32 v[80:81], v[196:197], v[136:137], v[80:81]
	v_pk_fma_f32 v[130:131], v[198:199], v[134:135], v[130:131]
	v_pk_fma_f32 v[132:133], v[200:201], v[136:137], v[132:133]
	v_pk_fma_f32 v[134:135], v[202:203], v[134:135], v[206:207]
	v_pk_fma_f32 v[136:137], v[204:205], v[136:137], v[208:209]
	v_pk_fma_f32 v[130:131], v[194:195], v[122:123], v[130:131]
	v_pk_fma_f32 v[132:133], v[196:197], v[124:125], v[132:133]
	v_pk_fma_f32 v[134:135], v[198:199], v[122:123], v[134:135]
	v_pk_fma_f32 v[136:137], v[200:201], v[124:125], v[136:137]
	v_pk_fma_f32 v[134:135], v[194:195], v[118:119], v[134:135]
	v_pk_fma_f32 v[136:137], v[196:197], v[120:121], v[136:137]
	s_cmp_lg_u32 s50, 0
	s_cbranch_scc1 .Lnepia_np0
	v_cmp_eq_u32_e32 vcc, 0, v224
	s_and_saveexec_b64 s[8:9], vcc
	s_add_u32 s48, s88, 0x2d00000
	s_addc_u32 s49, s89, 0
	global_store_dwordx4 v229, v[134:137], s[48:49] offset:0
	global_store_dwordx4 v231, v[130:133], s[48:49] offset:0
	s_or_b64 exec, exec, s[8:9]
	s_nop 1

.Lnepia_j2:
	v_mov_b32_dpp v162, v46 row_shr:1 row_mask:0xf bank_mask:0xf
	v_mov_b32_dpp v166, v142 row_shr:1 row_mask:0xf bank_mask:0xf
	v_mov_b32_dpp v163, v47 row_shr:1 row_mask:0xf bank_mask:0xf
	v_mov_b32_dpp v167, v143 row_shr:1 row_mask:0xf bank_mask:0xf
	v_mov_b32_dpp v164, v48 row_shr:1 row_mask:0xf bank_mask:0xf
	v_mov_b32_dpp v168, v144 row_shr:1 row_mask:0xf bank_mask:0xf
	v_mov_b32_dpp v165, v49 row_shr:1 row_mask:0xf bank_mask:0xf
	v_mov_b32_dpp v169, v145 row_shr:1 row_mask:0xf bank_mask:0xf
	v_pk_fma_f32 v[142:143], v[154:155], v[142:143], v[158:159]
	v_pk_fma_f32 v[144:145], v[156:157], v[144:145], v[160:161]
	v_pk_fma_f32 v[142:143], v[150:151], v[46:47], v[142:143]
	v_pk_fma_f32 v[144:145], v[152:153], v[48:49], v[144:145]
	v_pk_fma_f32 v[46:47], v[154:155], v[46:47], v[158:159]
	v_pk_fma_f32 v[48:49], v[156:157], v[48:49], v[160:161]
	v_pk_fma_f32 v[142:143], v[146:147], v[50:51], v[142:143]
	v_pk_fma_f32 v[144:145], v[148:149], v[52:53], v[144:145]
	v_pk_fma_f32 v[46:47], v[150:151], v[50:51], v[46:47]
	v_pk_fma_f32 v[48:49], v[152:153], v[52:53], v[48:49]
	v_pk_fma_f32 v[50:51], v[154:155], v[50:51], v[158:159]
	v_pk_fma_f32 v[52:53], v[156:157], v[52:53], v[160:161]
	v_pk_fma_f32 v[46:47], v[146:147], v[62:63], v[46:47]
	v_pk_fma_f32 v[48:49], v[148:149], v[64:65], v[48:49]
	v_pk_fma_f32 v[50:51], v[150:151], v[62:63], v[50:51]
	v_pk_fma_f32 v[52:53], v[152:153], v[64:65], v[52:53]
	v_pk_fma_f32 v[62:63], v[154:155], v[62:63], v[158:159]
	v_pk_fma_f32 v[64:65], v[156:157], v[64:65], v[160:161]
	v_pk_fma_f32 v[50:51], v[146:147], v[166:167], v[50:51]
	v_pk_fma_f32 v[52:53], v[148:149], v[168:169], v[52:53]
	v_pk_fma_f32 v[62:63], v[150:151], v[166:167], v[62:63]
	v_pk_fma_f32 v[64:65], v[152:153], v[168:169], v[64:65]
	v_pk_fma_f32 v[62:63], v[146:147], v[162:163], v[62:63]
	v_pk_fma_f32 v[64:65], v[148:149], v[164:165], v[64:65]
	s_cmp_lg_u32 s50, 0
	s_cbranch_scc1 .Lnepia_np1
	v_cmp_eq_u32_e32 vcc, 0, v224
	s_and_saveexec_b64 s[8:9], vcc
	s_add_u32 s48, s88, 0x2d00000
	s_addc_u32 s49, s89, 0
	global_store_dwordx4 v228, v[62:65], s[48:49] offset:0
	global_store_dwordx4 v230, v[50:53], s[48:49] offset:0
	s_or_b64 exec, exec, s[8:9]
	s_nop 1

.Lnepia_j3:
	v_mov_b32_dpp v118, v66 row_shr:1 row_mask:0xf bank_mask:0xf
	v_mov_b32_dpp v122, v98 row_shr:1 row_mask:0xf bank_mask:0xf
	v_mov_b32_dpp v119, v67 row_shr:1 row_mask:0xf bank_mask:0xf
	v_mov_b32_dpp v123, v99 row_shr:1 row_mask:0xf bank_mask:0xf
	v_mov_b32_dpp v120, v68 row_shr:1 row_mask:0xf bank_mask:0xf
	v_mov_b32_dpp v124, v100 row_shr:1 row_mask:0xf bank_mask:0xf
	v_mov_b32_dpp v121, v69 row_shr:1 row_mask:0xf bank_mask:0xf
	v_mov_b32_dpp v125, v101 row_shr:1 row_mask:0xf bank_mask:0xf
	v_pk_fma_f32 v[98:99], v[202:203], v[98:99], v[206:207]
	v_pk_fma_f32 v[100:101], v[204:205], v[100:101], v[208:209]
	v_pk_fma_f32 v[98:99], v[198:199], v[66:67], v[98:99]
	v_pk_fma_f32 v[100:101], v[200:201], v[68:69], v[100:101]
	v_pk_fma_f32 v[66:67], v[202:203], v[66:67], v[206:207]
	v_pk_fma_f32 v[68:69], v[204:205], v[68:69], v[208:209]
	v_pk_fma_f32 v[98:99], v[194:195], v[70:71], v[98:99]
	v_pk_fma_f32 v[100:101], v[196:197], v[72:73], v[100:101]
	v_pk_fma_f32 v[66:67], v[198:199], v[70:71], v[66:67]
	v_pk_fma_f32 v[68:69], v[200:201], v[72:73], v[68:69]
	v_pk_fma_f32 v[70:71], v[202:203], v[70:71], v[206:207]
	v_pk_fma_f32 v[72:73], v[204:205], v[72:73], v[208:209]
	v_pk_fma_f32 v[66:67], v[194:195], v[74:75], v[66:67]
	v_pk_fma_f32 v[68:69], v[196:197], v[76:77], v[68:69]
	v_pk_fma_f32 v[70:71], v[198:199], v[74:75], v[70:71]
	v_pk_fma_f32 v[72:73], v[200:201], v[76:77], v[72:73]
	v_pk_fma_f32 v[74:75], v[202:203], v[74:75], v[206:207]
	v_pk_fma_f32 v[76:77], v[204:205], v[76:77], v[208:209]
	v_pk_fma_f32 v[70:71], v[194:195], v[122:123], v[70:71]
	v_pk_fma_f32 v[72:73], v[196:197], v[124:125], v[72:73]
	v_pk_fma_f32 v[74:75], v[198:199], v[122:123], v[74:75]
	v_pk_fma_f32 v[76:77], v[200:201], v[124:125], v[76:77]
	v_pk_fma_f32 v[74:75], v[194:195], v[118:119], v[74:75]
	v_pk_fma_f32 v[76:77], v[196:197], v[120:121], v[76:77]
	s_cmp_lg_u32 s50, 0
	s_cbranch_scc1 .Lnepia_np2
	v_cmp_eq_u32_e32 vcc, 0, v224
	s_and_saveexec_b64 s[8:9], vcc
	s_add_u32 s48, s88, 0x2d00000
	s_addc_u32 s49, s89, 0
	global_store_dwordx4 v229, v[74:77], s[48:49] offset:16
	global_store_dwordx4 v231, v[70:73], s[48:49] offset:16
	s_or_b64 exec, exec, s[8:9]
	s_nop 1
.Lnepia_np2:
	s_waitcnt lgkmcnt(0)
	ds_read_b128 v[194:197], v226 offset:512
	ds_read_b128 v[198:201], v226 offset:1536
	ds_read_b128 v[202:205], v226 offset:2560
	ds_read_b128 v[206:209], v226 offset:3584
	ds_read_b128 v[118:121], v227 offset:4608
	ds_read_b128 v[122:125], v227 offset:5632
	v_mov_b32_dpp v162, v34 row_shr:1 row_mask:0xf bank_mask:0xf
	v_mov_b32_dpp v166, v82 row_shr:1 row_mask:0xf bank_mask:0xf
	v_mov_b32_dpp v163, v35 row_shr:1 row_mask:0xf bank_mask:0xf
	v_mov_b32_dpp v167, v83 row_shr:1 row_mask:0xf bank_mask:0xf
	v_mov_b32_dpp v164, v36 row_shr:1 row_mask:0xf bank_mask:0xf
	v_mov_b32_dpp v168, v84 row_shr:1 row_mask:0xf bank_mask:0xf
	v_mov_b32_dpp v165, v37 row_shr:1 row_mask:0xf bank_mask:0xf
	v_mov_b32_dpp v169, v85 row_shr:1 row_mask:0xf bank_mask:0xf
	v_pk_fma_f32 v[82:83], v[154:155], v[82:83], v[158:159]
	v_pk_fma_f32 v[84:85], v[156:157], v[84:85], v[160:161]
	v_pk_fma_f32 v[82:83], v[150:151], v[34:35], v[82:83]
	v_pk_fma_f32 v[84:85], v[152:153], v[36:37], v[84:85]
	v_pk_fma_f32 v[34:35], v[154:155], v[34:35], v[158:159]
	v_pk_fma_f32 v[36:37], v[156:157], v[36:37], v[160:161]
	v_pk_fma_f32 v[82:83], v[146:147], v[38:39], v[82:83]
	v_pk_fma_f32 v[84:85], v[148:149], v[40:41], v[84:85]
	v_pk_fma_f32 v[34:35], v[150:151], v[38:39], v[34:35]
	v_pk_fma_f32 v[36:37], v[152:153], v[40:41], v[36:37]
	v_pk_fma_f32 v[38:39], v[154:155], v[38:39], v[158:159]
	v_pk_fma_f32 v[40:41], v[156:157], v[40:41], v[160:161]
	v_pk_fma_f32 v[34:35], v[146:147], v[42:43], v[34:35]
	v_pk_fma_f32 v[36:37], v[148:149], v[44:45], v[36:37]
	v_pk_fma_f32 v[38:39], v[150:151], v[42:43], v[38:39]
	v_pk_fma_f32 v[40:41], v[152:153], v[44:45], v[40:41]
	v_pk_fma_f32 v[42:43], v[154:155], v[42:43], v[158:159]
	v_pk_fma_f32 v[44:45], v[156:157], v[44:45], v[160:161]
	v_pk_fma_f32 v[38:39], v[146:147], v[166:167], v[38:39]
	v_pk_fma_f32 v[40:41], v[148:149], v[168:169], v[40:41]
	v_pk_fma_f32 v[42:43], v[150:151], v[166:167], v[42:43]
	v_pk_fma_f32 v[44:45], v[152:153], v[168:169], v[44:45]
	v_pk_fma_f32 v[42:43], v[146:147], v[162:163], v[42:43]
	v_pk_fma_f32 v[44:45], v[148:149], v[164:165], v[44:45]
	s_cmp_lg_u32 s50, 0
	s_cbranch_scc1 .Lnepia_np3
	v_cmp_eq_u32_e32 vcc, 0, v224
	s_and_saveexec_b64 s[8:9], vcc
	s_add_u32 s48, s88, 0x2d00000
	s_addc_u32 s49, s89, 0
	global_store_dwordx4 v228, v[42:45], s[48:49] offset:16
	global_store_dwordx4 v230, v[38:41], s[48:49] offset:16
	s_or_b64 exec, exec, s[8:9]
	s_nop 1
.Lnepia_np3:
	v_pk_mul_f32 v[30:31], v[42:43], s[100:101]
	v_pk_mul_f32 v[32:33], v[44:45], s[100:101]
	v_pk_mul_f32 v[54:55], v[38:39], s[100:101]
	v_pk_mul_f32 v[56:57], v[40:41], s[100:101]
	v_exp_f32_e32 v30, v30
	v_exp_f32_e32 v31, v31
	v_exp_f32_e32 v32, v32
	v_exp_f32_e32 v33, v33
	v_exp_f32_e32 v54, v54
	v_exp_f32_e32 v55, v55
	v_exp_f32_e32 v56, v56
	v_exp_f32_e32 v57, v57
	v_pk_add_f32 v[30:31], v[30:31], s[98:99]
	v_pk_add_f32 v[32:33], v[32:33], s[98:99]
	v_pk_add_f32 v[54:55], v[54:55], s[98:99]
	v_pk_add_f32 v[56:57], v[56:57], s[98:99]
	v_rcp_f32_e32 v30, v30
	v_rcp_f32_e32 v31, v31
	v_rcp_f32_e32 v32, v32
	v_rcp_f32_e32 v33, v33
	v_rcp_f32_e32 v54, v54
	v_rcp_f32_e32 v55, v55
	v_rcp_f32_e32 v56, v56
	v_rcp_f32_e32 v57, v57
	v_pk_mul_f32 v[42:43], v[42:43], v[74:75]
	v_pk_mul_f32 v[44:45], v[44:45], v[76:77]
	v_pk_mul_f32 v[38:39], v[38:39], v[70:71]
	v_pk_mul_f32 v[40:41], v[40:41], v[72:73]
	v_pk_mul_f32 v[42:43], v[42:43], v[30:31]
	v_pk_mul_f32 v[44:45], v[44:45], v[32:33]
	v_pk_mul_f32 v[38:39], v[38:39], v[54:55]
	v_pk_mul_f32 v[40:41], v[40:41], v[56:57]
	v_pk_mul_f32 v[30:31], v[34:35], s[100:101]
	v_pk_mul_f32 v[32:33], v[36:37], s[100:101]
	v_pk_mul_f32 v[54:55], v[82:83], s[100:101]
	v_pk_mul_f32 v[56:57], v[84:85], s[100:101]
	v_exp_f32_e32 v30, v30
	v_exp_f32_e32 v31, v31
	v_exp_f32_e32 v32, v32
	v_exp_f32_e32 v33, v33
	v_exp_f32_e32 v54, v54
	v_exp_f32_e32 v55, v55
	v_exp_f32_e32 v56, v56
	v_exp_f32_e32 v57, v57
	v_pk_add_f32 v[30:31], v[30:31], s[98:99]
	v_pk_add_f32 v[32:33], v[32:33], s[98:99]
	v_pk_add_f32 v[54:55], v[54:55], s[98:99]
	v_pk_add_f32 v[56:57], v[56:57], s[98:99]
	v_rcp_f32_e32 v30, v30
	v_rcp_f32_e32 v31, v31
	v_rcp_f32_e32 v32, v32
	v_rcp_f32_e32 v33, v33
	v_rcp_f32_e32 v54, v54
	v_rcp_f32_e32 v55, v55
	v_rcp_f32_e32 v56, v56
	v_rcp_f32_e32 v57, v57
	v_pk_mul_f32 v[34:35], v[34:35], v[66:67]
	v_pk_mul_f32 v[36:37], v[36:37], v[68:69]
	v_pk_mul_f32 v[82:83], v[82:83], v[98:99]
	v_pk_mul_f32 v[84:85], v[84:85], v[100:101]
	v_pk_mul_f32 v[34:35], v[34:35], v[30:31]
	v_pk_mul_f32 v[36:37], v[36:37], v[32:33]
	v_pk_mul_f32 v[82:83], v[82:83], v[54:55]
	v_pk_mul_f32 v[84:85], v[84:85], v[56:57]
	s_add_u32 s48, s88, 0x9000000
	s_addc_u32 s49, s89, 0
	v_cvt_pk_bf16_f32 v134, v62, v63
	v_cvt_pk_bf16_f32 v135, v64, v65
	v_cvt_pk_bf16_f32 v136, v42, v43
	v_cvt_pk_bf16_f32 v137, v44, v45
	global_store_dwordx4 v244, v[134:137], s[48:49]
	v_add_u32_e32 v244, 0x1600, v244
	v_cvt_pk_bf16_f32 v74, v50, v51
	v_cvt_pk_bf16_f32 v75, v52, v53
	v_cvt_pk_bf16_f32 v76, v38, v39
	v_cvt_pk_bf16_f32 v77, v40, v41
	global_store_dwordx4 v244, v[74:77], s[48:49]
	v_add_u32_e32 v244, 0x1600, v244
	v_cvt_pk_bf16_f32 v134, v46, v47
	v_cvt_pk_bf16_f32 v135, v48, v49
	v_cvt_pk_bf16_f32 v136, v34, v35
	v_cvt_pk_bf16_f32 v137, v36, v37
	global_store_dwordx4 v244, v[134:137], s[48:49]
	v_add_u32_e32 v244, 0x1600, v244
	v_cvt_pk_bf16_f32 v74, v142, v143
	v_cvt_pk_bf16_f32 v75, v144, v145
	v_cvt_pk_bf16_f32 v76, v82, v83
	v_cvt_pk_bf16_f32 v77, v84, v85
	global_store_dwordx4 v244, v[74:77], s[48:49]
	v_add_u32_e32 v244, 0xffffbe00, v244
	s_waitcnt lgkmcnt(0)
	ds_read_b128 v[146:149], v226 offset:0
	ds_read_b128 v[150:153], v226 offset:1024
	ds_read_b128 v[154:157], v226 offset:2048
	ds_read_b128 v[158:161], v226 offset:3072
	ds_read_b128 v[162:165], v227 offset:4096
	ds_read_b128 v[166:169], v227 offset:5120
	v_mov_b32_dpp v118, v102 row_shr:1 row_mask:0xf bank_mask:0xf
	v_mov_b32_dpp v122, v126 row_shr:1 row_mask:0xf bank_mask:0xf
	v_mov_b32_dpp v119, v103 row_shr:1 row_mask:0xf bank_mask:0xf
	v_mov_b32_dpp v123, v127 row_shr:1 row_mask:0xf bank_mask:0xf
	v_mov_b32_dpp v120, v104 row_shr:1 row_mask:0xf bank_mask:0xf
	v_mov_b32_dpp v124, v128 row_shr:1 row_mask:0xf bank_mask:0xf
	v_mov_b32_dpp v121, v105 row_shr:1 row_mask:0xf bank_mask:0xf
	v_mov_b32_dpp v125, v129 row_shr:1 row_mask:0xf bank_mask:0xf
	v_pk_fma_f32 v[126:127], v[202:203], v[126:127], v[206:207]
	v_pk_fma_f32 v[128:129], v[204:205], v[128:129], v[208:209]
	v_pk_fma_f32 v[126:127], v[198:199], v[102:103], v[126:127]
	v_pk_fma_f32 v[128:129], v[200:201], v[104:105], v[128:129]
	v_pk_fma_f32 v[102:103], v[202:203], v[102:103], v[206:207]
	v_pk_fma_f32 v[104:105], v[204:205], v[104:105], v[208:209]
	v_pk_fma_f32 v[126:127], v[194:195], v[106:107], v[126:127]
	v_pk_fma_f32 v[128:129], v[196:197], v[108:109], v[128:129]
	v_pk_fma_f32 v[102:103], v[198:199], v[106:107], v[102:103]
	v_pk_fma_f32 v[104:105], v[200:201], v[108:109], v[104:105]
	v_pk_fma_f32 v[106:107], v[202:203], v[106:107], v[206:207]
	v_pk_fma_f32 v[108:109], v[204:205], v[108:109], v[208:209]
	v_pk_fma_f32 v[102:103], v[194:195], v[110:111], v[102:103]
	v_pk_fma_f32 v[104:105], v[196:197], v[112:113], v[104:105]
	v_pk_fma_f32 v[106:107], v[198:199], v[110:111], v[106:107]
	v_pk_fma_f32 v[108:109], v[200:201], v[112:113], v[108:109]
	v_pk_fma_f32 v[110:111], v[202:203], v[110:111], v[206:207]
	v_pk_fma_f32 v[112:113], v[204:205], v[112:113], v[208:209]
	v_pk_fma_f32 v[106:107], v[194:195], v[122:123], v[106:107]
	v_pk_fma_f32 v[108:109], v[196:197], v[124:125], v[108:109]
	v_pk_fma_f32 v[110:111], v[198:199], v[122:123], v[110:111]
	v_pk_fma_f32 v[112:113], v[200:201], v[124:125], v[112:113]
	v_pk_fma_f32 v[110:111], v[194:195], v[118:119], v[110:111]
	v_pk_fma_f32 v[112:113], v[196:197], v[120:121], v[112:113]
	s_waitcnt lgkmcnt(0)
	ds_read_b128 v[194:197], v226 offset:528
	ds_read_b128 v[198:201], v226 offset:1552
	ds_read_b128 v[202:205], v226 offset:2576
	ds_read_b128 v[206:209], v226 offset:3600
	ds_read_b128 v[118:121], v227 offset:4624
	ds_read_b128 v[122:125], v227 offset:5648
	v_mov_b32_dpp v162, v86 row_shr:1 row_mask:0xf bank_mask:0xf
	v_mov_b32_dpp v166, v114 row_shr:1 row_mask:0xf bank_mask:0xf
	v_mov_b32_dpp v163, v87 row_shr:1 row_mask:0xf bank_mask:0xf
	v_mov_b32_dpp v167, v115 row_shr:1 row_mask:0xf bank_mask:0xf
	v_mov_b32_dpp v164, v88 row_shr:1 row_mask:0xf bank_mask:0xf
	v_mov_b32_dpp v168, v116 row_shr:1 row_mask:0xf bank_mask:0xf
	v_mov_b32_dpp v165, v89 row_shr:1 row_mask:0xf bank_mask:0xf
	v_mov_b32_dpp v169, v117 row_shr:1 row_mask:0xf bank_mask:0xf
	v_pk_fma_f32 v[114:115], v[154:155], v[114:115], v[158:159]
	v_pk_fma_f32 v[116:117], v[156:157], v[116:117], v[160:161]
	v_pk_fma_f32 v[114:115], v[150:151], v[86:87], v[114:115]
	v_pk_fma_f32 v[116:117], v[152:153], v[88:89], v[116:117]
	v_pk_fma_f32 v[86:87], v[154:155], v[86:87], v[158:159]
	v_pk_fma_f32 v[88:89], v[156:157], v[88:89], v[160:161]
	v_pk_fma_f32 v[114:115], v[146:147], v[90:91], v[114:115]
	v_pk_fma_f32 v[116:117], v[148:149], v[92:93], v[116:117]
	v_pk_fma_f32 v[86:87], v[150:151], v[90:91], v[86:87]
	v_pk_fma_f32 v[88:89], v[152:153], v[92:93], v[88:89]
	v_pk_fma_f32 v[90:91], v[154:155], v[90:91], v[158:159]
	v_pk_fma_f32 v[92:93], v[156:157], v[92:93], v[160:161]
	v_pk_fma_f32 v[86:87], v[146:147], v[94:95], v[86:87]
	v_pk_fma_f32 v[88:89], v[148:149], v[96:97], v[88:89]
	v_pk_fma_f32 v[90:91], v[150:151], v[94:95], v[90:91]
	v_pk_fma_f32 v[92:93], v[152:153], v[96:97], v[92:93]
	v_pk_fma_f32 v[94:95], v[154:155], v[94:95], v[158:159]
	v_pk_fma_f32 v[96:97], v[156:157], v[96:97], v[160:161]
	v_pk_fma_f32 v[90:91], v[146:147], v[166:167], v[90:91]
	v_pk_fma_f32 v[92:93], v[148:149], v[168:169], v[92:93]
	v_pk_fma_f32 v[94:95], v[150:151], v[166:167], v[94:95]
	v_pk_fma_f32 v[96:97], v[152:153], v[168:169], v[96:97]
	v_pk_fma_f32 v[94:95], v[146:147], v[162:163], v[94:95]
	v_pk_fma_f32 v[96:97], v[148:149], v[164:165], v[96:97]
	v_pk_mul_f32 v[30:31], v[94:95], s[100:101]
	v_pk_mul_f32 v[32:33], v[96:97], s[100:101]
	v_pk_mul_f32 v[54:55], v[90:91], s[100:101]
	v_pk_mul_f32 v[56:57], v[92:93], s[100:101]
	v_exp_f32_e32 v30, v30
	v_exp_f32_e32 v31, v31
	v_exp_f32_e32 v32, v32
	v_exp_f32_e32 v33, v33
	v_exp_f32_e32 v54, v54
	v_exp_f32_e32 v55, v55
	v_exp_f32_e32 v56, v56
	v_exp_f32_e32 v57, v57
	v_pk_add_f32 v[30:31], v[30:31], s[98:99]
	v_pk_add_f32 v[32:33], v[32:33], s[98:99]
	v_pk_add_f32 v[54:55], v[54:55], s[98:99]
	v_pk_add_f32 v[56:57], v[56:57], s[98:99]
	v_rcp_f32_e32 v30, v30
	v_rcp_f32_e32 v31, v31
	v_rcp_f32_e32 v32, v32
	v_rcp_f32_e32 v33, v33
	v_rcp_f32_e32 v54, v54
	v_rcp_f32_e32 v55, v55
	v_rcp_f32_e32 v56, v56
	v_rcp_f32_e32 v57, v57
	v_pk_mul_f32 v[94:95], v[94:95], v[110:111]
	v_pk_mul_f32 v[96:97], v[96:97], v[112:113]
	v_pk_mul_f32 v[90:91], v[90:91], v[106:107]
	v_pk_mul_f32 v[92:93], v[92:93], v[108:109]
	v_pk_mul_f32 v[94:95], v[94:95], v[30:31]
	v_pk_mul_f32 v[96:97], v[96:97], v[32:33]
	v_pk_mul_f32 v[90:91], v[90:91], v[54:55]
	v_pk_mul_f32 v[92:93], v[92:93], v[56:57]
	v_pk_mul_f32 v[30:31], v[86:87], s[100:101]
	v_pk_mul_f32 v[32:33], v[88:89], s[100:101]
	v_pk_mul_f32 v[54:55], v[114:115], s[100:101]
	v_pk_mul_f32 v[56:57], v[116:117], s[100:101]
	v_exp_f32_e32 v30, v30
	v_exp_f32_e32 v31, v31
	v_exp_f32_e32 v32, v32
	v_exp_f32_e32 v33, v33
	v_exp_f32_e32 v54, v54
	v_exp_f32_e32 v55, v55
	v_exp_f32_e32 v56, v56
	v_exp_f32_e32 v57, v57
	v_pk_add_f32 v[30:31], v[30:31], s[98:99]
	v_pk_add_f32 v[32:33], v[32:33], s[98:99]
	v_pk_add_f32 v[54:55], v[54:55], s[98:99]
	v_pk_add_f32 v[56:57], v[56:57], s[98:99]
	v_rcp_f32_e32 v30, v30
	v_rcp_f32_e32 v31, v31
	v_rcp_f32_e32 v32, v32
	v_rcp_f32_e32 v33, v33
	v_rcp_f32_e32 v54, v54
	v_rcp_f32_e32 v55, v55
	v_rcp_f32_e32 v56, v56
	v_rcp_f32_e32 v57, v57
	v_pk_mul_f32 v[86:87], v[86:87], v[102:103]
	v_pk_mul_f32 v[88:89], v[88:89], v[104:105]
	v_pk_mul_f32 v[114:115], v[114:115], v[126:127]
	v_pk_mul_f32 v[116:117], v[116:117], v[128:129]
	v_pk_mul_f32 v[86:87], v[86:87], v[30:31]
	v_pk_mul_f32 v[88:89], v[88:89], v[32:33]
	v_pk_mul_f32 v[114:115], v[114:115], v[54:55]
	v_pk_mul_f32 v[116:117], v[116:117], v[56:57]
	s_waitcnt lgkmcnt(0)
	ds_read_b128 v[146:149], v226 offset:16
	ds_read_b128 v[150:153], v226 offset:1040
	ds_read_b128 v[154:157], v226 offset:2064
	ds_read_b128 v[158:161], v226 offset:3088
	ds_read_b128 v[162:165], v227 offset:4112
	ds_read_b128 v[166:169], v227 offset:5136
	v_mov_b32_dpp v118, v14 row_shr:1 row_mask:0xf bank_mask:0xf
	v_mov_b32_dpp v122, v58 row_shr:1 row_mask:0xf bank_mask:0xf
	v_mov_b32_dpp v119, v15 row_shr:1 row_mask:0xf bank_mask:0xf
	v_mov_b32_dpp v123, v59 row_shr:1 row_mask:0xf bank_mask:0xf
	v_mov_b32_dpp v120, v16 row_shr:1 row_mask:0xf bank_mask:0xf
	v_mov_b32_dpp v124, v60 row_shr:1 row_mask:0xf bank_mask:0xf
	v_mov_b32_dpp v121, v17 row_shr:1 row_mask:0xf bank_mask:0xf
	v_mov_b32_dpp v125, v61 row_shr:1 row_mask:0xf bank_mask:0xf
	v_pk_fma_f32 v[58:59], v[202:203], v[58:59], v[206:207]
	v_pk_fma_f32 v[60:61], v[204:205], v[60:61], v[208:209]
	v_pk_fma_f32 v[58:59], v[198:199], v[14:15], v[58:59]
	v_pk_fma_f32 v[60:61], v[200:201], v[16:17], v[60:61]
	v_pk_fma_f32 v[14:15], v[202:203], v[14:15], v[206:207]
	v_pk_fma_f32 v[16:17], v[204:205], v[16:17], v[208:209]
	v_pk_fma_f32 v[58:59], v[194:195], v[18:19], v[58:59]
	v_pk_fma_f32 v[60:61], v[196:197], v[20:21], v[60:61]
	v_pk_fma_f32 v[14:15], v[198:199], v[18:19], v[14:15]
	v_pk_fma_f32 v[16:17], v[200:201], v[20:21], v[16:17]
	v_pk_fma_f32 v[18:19], v[202:203], v[18:19], v[206:207]
	v_pk_fma_f32 v[20:21], v[204:205], v[20:21], v[208:209]
	v_pk_fma_f32 v[14:15], v[194:195], v[22:23], v[14:15]
	v_pk_fma_f32 v[16:17], v[196:197], v[24:25], v[16:17]
	v_pk_fma_f32 v[18:19], v[198:199], v[22:23], v[18:19]
	v_pk_fma_f32 v[20:21], v[200:201], v[24:25], v[20:21]
	v_pk_fma_f32 v[22:23], v[202:203], v[22:23], v[206:207]
	v_pk_fma_f32 v[24:25], v[204:205], v[24:25], v[208:209]
	v_pk_fma_f32 v[18:19], v[194:195], v[122:123], v[18:19]
	v_pk_fma_f32 v[20:21], v[196:197], v[124:125], v[20:21]
	v_pk_fma_f32 v[22:23], v[198:199], v[122:123], v[22:23]
	v_pk_fma_f32 v[24:25], v[200:201], v[124:125], v[24:25]
	v_pk_fma_f32 v[22:23], v[194:195], v[118:119], v[22:23]
	v_pk_fma_f32 v[24:25], v[196:197], v[120:121], v[24:25]
	s_waitcnt lgkmcnt(0)
	v_mov_b32_dpp v162, v2 row_shr:1 row_mask:0xf bank_mask:0xf
	v_mov_b32_dpp v166, v26 row_shr:1 row_mask:0xf bank_mask:0xf
	v_mov_b32_dpp v163, v3 row_shr:1 row_mask:0xf bank_mask:0xf
	v_mov_b32_dpp v167, v27 row_shr:1 row_mask:0xf bank_mask:0xf
	v_mov_b32_dpp v164, v4 row_shr:1 row_mask:0xf bank_mask:0xf
	v_mov_b32_dpp v168, v28 row_shr:1 row_mask:0xf bank_mask:0xf
	v_mov_b32_dpp v165, v5 row_shr:1 row_mask:0xf bank_mask:0xf
	v_mov_b32_dpp v169, v29 row_shr:1 row_mask:0xf bank_mask:0xf
	v_pk_fma_f32 v[26:27], v[154:155], v[26:27], v[158:159]
	v_pk_fma_f32 v[28:29], v[156:157], v[28:29], v[160:161]
	v_pk_fma_f32 v[26:27], v[150:151], v[2:3], v[26:27]
	v_pk_fma_f32 v[28:29], v[152:153], v[4:5], v[28:29]
	v_pk_fma_f32 v[2:3], v[154:155], v[2:3], v[158:159]
	v_pk_fma_f32 v[4:5], v[156:157], v[4:5], v[160:161]
	v_pk_fma_f32 v[26:27], v[146:147], v[6:7], v[26:27]
	v_pk_fma_f32 v[28:29], v[148:149], v[8:9], v[28:29]
	v_pk_fma_f32 v[2:3], v[150:151], v[6:7], v[2:3]
	v_pk_fma_f32 v[4:5], v[152:153], v[8:9], v[4:5]
	v_pk_fma_f32 v[6:7], v[154:155], v[6:7], v[158:159]
	v_pk_fma_f32 v[8:9], v[156:157], v[8:9], v[160:161]
	v_pk_fma_f32 v[2:3], v[146:147], v[10:11], v[2:3]
	v_pk_fma_f32 v[4:5], v[148:149], v[12:13], v[4:5]
	v_pk_fma_f32 v[6:7], v[150:151], v[10:11], v[6:7]
	v_pk_fma_f32 v[8:9], v[152:153], v[12:13], v[8:9]
	v_pk_fma_f32 v[10:11], v[154:155], v[10:11], v[158:159]
	v_pk_fma_f32 v[12:13], v[156:157], v[12:13], v[160:161]
	v_pk_fma_f32 v[6:7], v[146:147], v[166:167], v[6:7]
	v_pk_fma_f32 v[8:9], v[148:149], v[168:169], v[8:9]
	v_pk_fma_f32 v[10:11], v[150:151], v[166:167], v[10:11]
	v_pk_fma_f32 v[12:13], v[152:153], v[168:169], v[12:13]
	v_pk_fma_f32 v[10:11], v[146:147], v[162:163], v[10:11]
	v_pk_fma_f32 v[12:13], v[148:149], v[164:165], v[12:13]
	v_pk_mul_f32 v[30:31], v[10:11], s[100:101]
	v_pk_mul_f32 v[32:33], v[12:13], s[100:101]
	v_pk_mul_f32 v[54:55], v[6:7], s[100:101]
	v_pk_mul_f32 v[56:57], v[8:9], s[100:101]
	v_exp_f32_e32 v30, v30
	v_exp_f32_e32 v31, v31
	v_exp_f32_e32 v32, v32
	v_exp_f32_e32 v33, v33
	v_exp_f32_e32 v54, v54
	v_exp_f32_e32 v55, v55
	v_exp_f32_e32 v56, v56
	v_exp_f32_e32 v57, v57
	v_pk_add_f32 v[30:31], v[30:31], s[98:99]
	v_pk_add_f32 v[32:33], v[32:33], s[98:99]
	v_pk_add_f32 v[54:55], v[54:55], s[98:99]
	v_pk_add_f32 v[56:57], v[56:57], s[98:99]
	v_rcp_f32_e32 v30, v30
	v_rcp_f32_e32 v31, v31
	v_rcp_f32_e32 v32, v32
	v_rcp_f32_e32 v33, v33
	v_rcp_f32_e32 v54, v54
	v_rcp_f32_e32 v55, v55
	v_rcp_f32_e32 v56, v56
	v_rcp_f32_e32 v57, v57
	v_pk_mul_f32 v[10:11], v[10:11], v[22:23]
	v_pk_mul_f32 v[12:13], v[12:13], v[24:25]
	v_pk_mul_f32 v[6:7], v[6:7], v[18:19]
	v_pk_mul_f32 v[8:9], v[8:9], v[20:21]
	v_pk_mul_f32 v[10:11], v[10:11], v[30:31]
	v_pk_mul_f32 v[12:13], v[12:13], v[32:33]
	v_pk_mul_f32 v[6:7], v[6:7], v[54:55]
	v_pk_mul_f32 v[8:9], v[8:9], v[56:57]
	v_pk_mul_f32 v[30:31], v[2:3], s[100:101]
	v_pk_mul_f32 v[32:33], v[4:5], s[100:101]
	v_pk_mul_f32 v[54:55], v[26:27], s[100:101]
	v_pk_mul_f32 v[56:57], v[28:29], s[100:101]
	v_exp_f32_e32 v30, v30
	v_exp_f32_e32 v31, v31
	v_exp_f32_e32 v32, v32
	v_exp_f32_e32 v33, v33
	v_exp_f32_e32 v54, v54
	v_exp_f32_e32 v55, v55
	v_exp_f32_e32 v56, v56
	v_exp_f32_e32 v57, v57
	v_pk_add_f32 v[30:31], v[30:31], s[98:99]
	v_pk_add_f32 v[32:33], v[32:33], s[98:99]
	v_pk_add_f32 v[54:55], v[54:55], s[98:99]
	v_pk_add_f32 v[56:57], v[56:57], s[98:99]
	v_rcp_f32_e32 v30, v30
	v_rcp_f32_e32 v31, v31
	v_rcp_f32_e32 v32, v32
	v_rcp_f32_e32 v33, v33
	v_rcp_f32_e32 v54, v54
	v_rcp_f32_e32 v55, v55
	v_rcp_f32_e32 v56, v56
	v_rcp_f32_e32 v57, v57
	v_pk_mul_f32 v[2:3], v[2:3], v[14:15]
	v_pk_mul_f32 v[4:5], v[4:5], v[16:17]
	v_pk_mul_f32 v[26:27], v[26:27], v[58:59]
	v_pk_mul_f32 v[28:29], v[28:29], v[60:61]
	v_pk_mul_f32 v[2:3], v[2:3], v[30:31]
	v_pk_mul_f32 v[4:5], v[4:5], v[32:33]
	v_pk_mul_f32 v[26:27], v[26:27], v[54:55]
	v_pk_mul_f32 v[28:29], v[28:29], v[56:57]
	v_add_u32_e32 v244, 0xb0000, v244
	v_cvt_pk_bf16_f32 v110, v94, v95
	v_cvt_pk_bf16_f32 v111, v96, v97
	v_cvt_pk_bf16_f32 v112, v10, v11
	v_cvt_pk_bf16_f32 v113, v12, v13
	global_store_dwordx4 v244, v[110:113], s[48:49]
	v_add_u32_e32 v244, 0x1600, v244
	v_cvt_pk_bf16_f32 v22, v90, v91
	v_cvt_pk_bf16_f32 v23, v92, v93
	v_cvt_pk_bf16_f32 v24, v6, v7
	v_cvt_pk_bf16_f32 v25, v8, v9
	global_store_dwordx4 v244, v[22:25], s[48:49]
	v_add_u32_e32 v244, 0x1600, v244
	v_cvt_pk_bf16_f32 v110, v86, v87
	v_cvt_pk_bf16_f32 v111, v88, v89
	v_cvt_pk_bf16_f32 v112, v2, v3
	v_cvt_pk_bf16_f32 v113, v4, v5
	global_store_dwordx4 v244, v[110:113], s[48:49]
	v_add_u32_e32 v244, 0x1600, v244
	v_cvt_pk_bf16_f32 v22, v114, v115
	v_cvt_pk_bf16_f32 v23, v116, v117
	v_cvt_pk_bf16_f32 v24, v26, v27
	v_cvt_pk_bf16_f32 v25, v28, v29
	global_store_dwordx4 v244, v[22:25], s[48:49]
	s_cmp_lg_u32 s50, 1
	s_cselect_b64 s[8:9], -1, 0
	s_andn2_b64 vcc, exec, s[4:5]
	s_mov_b64 s[4:5], -1
	s_cbranch_vccnz .LBB0_553
	s_andn2_b64 vcc, exec, s[16:17]
	s_mov_b32 s3, s40
	s_mov_b64 s[28:29], s[94:95]
	s_mov_b64 s[4:5], s[36:37]
	s_cbranch_vccnz .LBB0_590
	s_ashr_i32 s3, s40, 5
	s_mul_hi_i32 s4, s3, 0x5800
	s_mulk_i32 s3, 0x5800
	v_readlane_b32 s5, v255, 14
	s_add_u32 s28, s5, s3
	v_readlane_b32 s3, v255, 15
	s_addc_u32 s29, s3, s4
	s_mov_b32 s3, s38
	s_mov_b64 s[4:5], s[62:63]

.Lnepib_j1:
	v_mov_b32_dpp v118, v78 row_shr:1 row_mask:0xf bank_mask:0xf
	v_mov_b32_dpp v122, v138 row_shr:1 row_mask:0xf bank_mask:0xf
	v_mov_b32_dpp v119, v79 row_shr:1 row_mask:0xf bank_mask:0xf
	v_mov_b32_dpp v123, v139 row_shr:1 row_mask:0xf bank_mask:0xf
	v_mov_b32_dpp v120, v80 row_shr:1 row_mask:0xf bank_mask:0xf
	v_mov_b32_dpp v124, v140 row_shr:1 row_mask:0xf bank_mask:0xf
	v_mov_b32_dpp v121, v81 row_shr:1 row_mask:0xf bank_mask:0xf
	v_mov_b32_dpp v125, v141 row_shr:1 row_mask:0xf bank_mask:0xf
	v_pk_fma_f32 v[138:139], v[204:205], v[138:139], v[208:209]
	v_pk_fma_f32 v[140:141], v[206:207], v[140:141], v[210:211]
	v_pk_fma_f32 v[138:139], v[200:201], v[78:79], v[138:139]
	v_pk_fma_f32 v[140:141], v[202:203], v[80:81], v[140:141]
	v_pk_fma_f32 v[78:79], v[204:205], v[78:79], v[208:209]
	v_pk_fma_f32 v[80:81], v[206:207], v[80:81], v[210:211]
	v_pk_fma_f32 v[138:139], v[196:197], v[130:131], v[138:139]
	v_pk_fma_f32 v[140:141], v[198:199], v[132:133], v[140:141]
	v_pk_fma_f32 v[78:79], v[200:201], v[130:131], v[78:79]
	v_pk_fma_f32 v[80:81], v[202:203], v[132:133], v[80:81]
	v_pk_fma_f32 v[130:131], v[204:205], v[130:131], v[208:209]
	v_pk_fma_f32 v[132:133], v[206:207], v[132:133], v[210:211]
	v_pk_fma_f32 v[78:79], v[196:197], v[134:135], v[78:79]
	v_pk_fma_f32 v[80:81], v[198:199], v[136:137], v[80:81]
	v_pk_fma_f32 v[130:131], v[200:201], v[134:135], v[130:131]
	v_pk_fma_f32 v[132:133], v[202:203], v[136:137], v[132:133]
	v_pk_fma_f32 v[134:135], v[204:205], v[134:135], v[208:209]
	v_pk_fma_f32 v[136:137], v[206:207], v[136:137], v[210:211]
	v_pk_fma_f32 v[130:131], v[196:197], v[122:123], v[130:131]
	v_pk_fma_f32 v[132:133], v[198:199], v[124:125], v[132:133]
	v_pk_fma_f32 v[134:135], v[200:201], v[122:123], v[134:135]
	v_pk_fma_f32 v[136:137], v[202:203], v[124:125], v[136:137]
	v_pk_fma_f32 v[134:135], v[196:197], v[118:119], v[134:135]
	v_pk_fma_f32 v[136:137], v[198:199], v[120:121], v[136:137]
	s_cmp_lg_u32 s54, 0
	s_cbranch_scc1 .Lnepib_np0
	v_cmp_eq_u32_e32 vcc, 0, v224
	s_and_saveexec_b64 s[8:9], vcc
	s_add_u32 s52, s88, 0x2d00000
	s_addc_u32 s53, s89, 0
	global_store_dwordx4 v229, v[134:137], s[52:53] offset:0
	global_store_dwordx4 v231, v[130:133], s[52:53] offset:0
	s_or_b64 exec, exec, s[8:9]
	s_nop 1

.Lnepib_j2:
	v_mov_b32_dpp v162, v46 row_shr:1 row_mask:0xf bank_mask:0xf
	v_mov_b32_dpp v166, v142 row_shr:1 row_mask:0xf bank_mask:0xf
	v_mov_b32_dpp v163, v47 row_shr:1 row_mask:0xf bank_mask:0xf
	v_mov_b32_dpp v167, v143 row_shr:1 row_mask:0xf bank_mask:0xf
	v_mov_b32_dpp v164, v48 row_shr:1 row_mask:0xf bank_mask:0xf
	v_mov_b32_dpp v168, v144 row_shr:1 row_mask:0xf bank_mask:0xf
	v_mov_b32_dpp v165, v49 row_shr:1 row_mask:0xf bank_mask:0xf
	v_mov_b32_dpp v169, v145 row_shr:1 row_mask:0xf bank_mask:0xf
	v_pk_fma_f32 v[142:143], v[154:155], v[142:143], v[158:159]
	v_pk_fma_f32 v[144:145], v[156:157], v[144:145], v[160:161]
	v_pk_fma_f32 v[142:143], v[150:151], v[46:47], v[142:143]
	v_pk_fma_f32 v[144:145], v[152:153], v[48:49], v[144:145]
	v_pk_fma_f32 v[46:47], v[154:155], v[46:47], v[158:159]
	v_pk_fma_f32 v[48:49], v[156:157], v[48:49], v[160:161]
	v_pk_fma_f32 v[142:143], v[146:147], v[50:51], v[142:143]
	v_pk_fma_f32 v[144:145], v[148:149], v[52:53], v[144:145]
	v_pk_fma_f32 v[46:47], v[150:151], v[50:51], v[46:47]
	v_pk_fma_f32 v[48:49], v[152:153], v[52:53], v[48:49]
	v_pk_fma_f32 v[50:51], v[154:155], v[50:51], v[158:159]
	v_pk_fma_f32 v[52:53], v[156:157], v[52:53], v[160:161]
	v_pk_fma_f32 v[46:47], v[146:147], v[62:63], v[46:47]
	v_pk_fma_f32 v[48:49], v[148:149], v[64:65], v[48:49]
	v_pk_fma_f32 v[50:51], v[150:151], v[62:63], v[50:51]
	v_pk_fma_f32 v[52:53], v[152:153], v[64:65], v[52:53]
	v_pk_fma_f32 v[62:63], v[154:155], v[62:63], v[158:159]
	v_pk_fma_f32 v[64:65], v[156:157], v[64:65], v[160:161]
	v_pk_fma_f32 v[50:51], v[146:147], v[166:167], v[50:51]
	v_pk_fma_f32 v[52:53], v[148:149], v[168:169], v[52:53]
	v_pk_fma_f32 v[62:63], v[150:151], v[166:167], v[62:63]
	v_pk_fma_f32 v[64:65], v[152:153], v[168:169], v[64:65]
	v_pk_fma_f32 v[62:63], v[146:147], v[162:163], v[62:63]
	v_pk_fma_f32 v[64:65], v[148:149], v[164:165], v[64:65]
	s_cmp_lg_u32 s54, 0
	s_cbranch_scc1 .Lnepib_np1
	v_cmp_eq_u32_e32 vcc, 0, v224
	s_and_saveexec_b64 s[8:9], vcc
	s_add_u32 s52, s88, 0x2d00000
	s_addc_u32 s53, s89, 0
	global_store_dwordx4 v228, v[62:65], s[52:53] offset:0
	global_store_dwordx4 v230, v[50:53], s[52:53] offset:0
	s_or_b64 exec, exec, s[8:9]
	s_nop 1

.Lnepib_j3:
	v_mov_b32_dpp v118, v66 row_shr:1 row_mask:0xf bank_mask:0xf
	v_mov_b32_dpp v122, v98 row_shr:1 row_mask:0xf bank_mask:0xf
	v_mov_b32_dpp v119, v67 row_shr:1 row_mask:0xf bank_mask:0xf
	v_mov_b32_dpp v123, v99 row_shr:1 row_mask:0xf bank_mask:0xf
	v_mov_b32_dpp v120, v68 row_shr:1 row_mask:0xf bank_mask:0xf
	v_mov_b32_dpp v124, v100 row_shr:1 row_mask:0xf bank_mask:0xf
	v_mov_b32_dpp v121, v69 row_shr:1 row_mask:0xf bank_mask:0xf
	v_mov_b32_dpp v125, v101 row_shr:1 row_mask:0xf bank_mask:0xf
	v_pk_fma_f32 v[98:99], v[204:205], v[98:99], v[208:209]
	v_pk_fma_f32 v[100:101], v[206:207], v[100:101], v[210:211]
	v_pk_fma_f32 v[98:99], v[200:201], v[66:67], v[98:99]
	v_pk_fma_f32 v[100:101], v[202:203], v[68:69], v[100:101]
	v_pk_fma_f32 v[66:67], v[204:205], v[66:67], v[208:209]
	v_pk_fma_f32 v[68:69], v[206:207], v[68:69], v[210:211]
	v_pk_fma_f32 v[98:99], v[196:197], v[70:71], v[98:99]
	v_pk_fma_f32 v[100:101], v[198:199], v[72:73], v[100:101]
	v_pk_fma_f32 v[66:67], v[200:201], v[70:71], v[66:67]
	v_pk_fma_f32 v[68:69], v[202:203], v[72:73], v[68:69]
	v_pk_fma_f32 v[70:71], v[204:205], v[70:71], v[208:209]
	v_pk_fma_f32 v[72:73], v[206:207], v[72:73], v[210:211]
	v_pk_fma_f32 v[66:67], v[196:197], v[74:75], v[66:67]
	v_pk_fma_f32 v[68:69], v[198:199], v[76:77], v[68:69]
	v_pk_fma_f32 v[70:71], v[200:201], v[74:75], v[70:71]
	v_pk_fma_f32 v[72:73], v[202:203], v[76:77], v[72:73]
	v_pk_fma_f32 v[74:75], v[204:205], v[74:75], v[208:209]
	v_pk_fma_f32 v[76:77], v[206:207], v[76:77], v[210:211]
	v_pk_fma_f32 v[70:71], v[196:197], v[122:123], v[70:71]
	v_pk_fma_f32 v[72:73], v[198:199], v[124:125], v[72:73]
	v_pk_fma_f32 v[74:75], v[200:201], v[122:123], v[74:75]
	v_pk_fma_f32 v[76:77], v[202:203], v[124:125], v[76:77]
	v_pk_fma_f32 v[74:75], v[196:197], v[118:119], v[74:75]
	v_pk_fma_f32 v[76:77], v[198:199], v[120:121], v[76:77]
	s_cmp_lg_u32 s54, 0
	s_cbranch_scc1 .Lnepib_np2
	v_cmp_eq_u32_e32 vcc, 0, v224
	s_and_saveexec_b64 s[8:9], vcc
	s_add_u32 s52, s88, 0x2d00000
	s_addc_u32 s53, s89, 0
	global_store_dwordx4 v229, v[74:77], s[52:53] offset:16
	global_store_dwordx4 v231, v[70:73], s[52:53] offset:16
	s_or_b64 exec, exec, s[8:9]
	s_nop 1
.Lnepib_np2:
	s_waitcnt lgkmcnt(0)
	ds_read_b128 v[196:199], v226 offset:512
	ds_read_b128 v[200:203], v226 offset:1536
	ds_read_b128 v[204:207], v226 offset:2560
	ds_read_b128 v[208:211], v226 offset:3584
	ds_read_b128 v[118:121], v227 offset:4608
	ds_read_b128 v[122:125], v227 offset:5632
	v_mov_b32_dpp v162, v34 row_shr:1 row_mask:0xf bank_mask:0xf
	v_mov_b32_dpp v166, v82 row_shr:1 row_mask:0xf bank_mask:0xf
	v_mov_b32_dpp v163, v35 row_shr:1 row_mask:0xf bank_mask:0xf
	v_mov_b32_dpp v167, v83 row_shr:1 row_mask:0xf bank_mask:0xf
	v_mov_b32_dpp v164, v36 row_shr:1 row_mask:0xf bank_mask:0xf
	v_mov_b32_dpp v168, v84 row_shr:1 row_mask:0xf bank_mask:0xf
	v_mov_b32_dpp v165, v37 row_shr:1 row_mask:0xf bank_mask:0xf
	v_mov_b32_dpp v169, v85 row_shr:1 row_mask:0xf bank_mask:0xf
	v_pk_fma_f32 v[82:83], v[154:155], v[82:83], v[158:159]
	v_pk_fma_f32 v[84:85], v[156:157], v[84:85], v[160:161]
	v_pk_fma_f32 v[82:83], v[150:151], v[34:35], v[82:83]
	v_pk_fma_f32 v[84:85], v[152:153], v[36:37], v[84:85]
	v_pk_fma_f32 v[34:35], v[154:155], v[34:35], v[158:159]
	v_pk_fma_f32 v[36:37], v[156:157], v[36:37], v[160:161]
	v_pk_fma_f32 v[82:83], v[146:147], v[38:39], v[82:83]
	v_pk_fma_f32 v[84:85], v[148:149], v[40:41], v[84:85]
	v_pk_fma_f32 v[34:35], v[150:151], v[38:39], v[34:35]
	v_pk_fma_f32 v[36:37], v[152:153], v[40:41], v[36:37]
	v_pk_fma_f32 v[38:39], v[154:155], v[38:39], v[158:159]
	v_pk_fma_f32 v[40:41], v[156:157], v[40:41], v[160:161]
	v_pk_fma_f32 v[34:35], v[146:147], v[42:43], v[34:35]
	v_pk_fma_f32 v[36:37], v[148:149], v[44:45], v[36:37]
	v_pk_fma_f32 v[38:39], v[150:151], v[42:43], v[38:39]
	v_pk_fma_f32 v[40:41], v[152:153], v[44:45], v[40:41]
	v_pk_fma_f32 v[42:43], v[154:155], v[42:43], v[158:159]
	v_pk_fma_f32 v[44:45], v[156:157], v[44:45], v[160:161]
	v_pk_fma_f32 v[38:39], v[146:147], v[166:167], v[38:39]
	v_pk_fma_f32 v[40:41], v[148:149], v[168:169], v[40:41]
	v_pk_fma_f32 v[42:43], v[150:151], v[166:167], v[42:43]
	v_pk_fma_f32 v[44:45], v[152:153], v[168:169], v[44:45]
	v_pk_fma_f32 v[42:43], v[146:147], v[162:163], v[42:43]
	v_pk_fma_f32 v[44:45], v[148:149], v[164:165], v[44:45]
	s_cmp_lg_u32 s54, 0
	s_cbranch_scc1 .Lnepib_np3
	v_cmp_eq_u32_e32 vcc, 0, v224
	s_and_saveexec_b64 s[8:9], vcc
	s_add_u32 s52, s88, 0x2d00000
	s_addc_u32 s53, s89, 0
	global_store_dwordx4 v228, v[42:45], s[52:53] offset:16
	global_store_dwordx4 v230, v[38:41], s[52:53] offset:16
	s_or_b64 exec, exec, s[8:9]
	s_nop 1
.Lnepib_np3:
	v_pk_mul_f32 v[30:31], v[42:43], s[100:101]
	v_pk_mul_f32 v[32:33], v[44:45], s[100:101]
	v_pk_mul_f32 v[54:55], v[38:39], s[100:101]
	v_pk_mul_f32 v[56:57], v[40:41], s[100:101]
	v_exp_f32_e32 v30, v30
	v_exp_f32_e32 v31, v31
	v_exp_f32_e32 v32, v32
	v_exp_f32_e32 v33, v33
	v_exp_f32_e32 v54, v54
	v_exp_f32_e32 v55, v55
	v_exp_f32_e32 v56, v56
	v_exp_f32_e32 v57, v57
	v_pk_add_f32 v[30:31], v[30:31], s[98:99]
	v_pk_add_f32 v[32:33], v[32:33], s[98:99]
	v_pk_add_f32 v[54:55], v[54:55], s[98:99]
	v_pk_add_f32 v[56:57], v[56:57], s[98:99]
	v_rcp_f32_e32 v30, v30
	v_rcp_f32_e32 v31, v31
	v_rcp_f32_e32 v32, v32
	v_rcp_f32_e32 v33, v33
	v_rcp_f32_e32 v54, v54
	v_rcp_f32_e32 v55, v55
	v_rcp_f32_e32 v56, v56
	v_rcp_f32_e32 v57, v57
	v_pk_mul_f32 v[42:43], v[42:43], v[74:75]
	v_pk_mul_f32 v[44:45], v[44:45], v[76:77]
	v_pk_mul_f32 v[38:39], v[38:39], v[70:71]
	v_pk_mul_f32 v[40:41], v[40:41], v[72:73]
	v_pk_mul_f32 v[42:43], v[42:43], v[30:31]
	v_pk_mul_f32 v[44:45], v[44:45], v[32:33]
	v_pk_mul_f32 v[38:39], v[38:39], v[54:55]
	v_pk_mul_f32 v[40:41], v[40:41], v[56:57]
	v_pk_mul_f32 v[30:31], v[34:35], s[100:101]
	v_pk_mul_f32 v[32:33], v[36:37], s[100:101]
	v_pk_mul_f32 v[54:55], v[82:83], s[100:101]
	v_pk_mul_f32 v[56:57], v[84:85], s[100:101]
	v_exp_f32_e32 v30, v30
	v_exp_f32_e32 v31, v31
	v_exp_f32_e32 v32, v32
	v_exp_f32_e32 v33, v33
	v_exp_f32_e32 v54, v54
	v_exp_f32_e32 v55, v55
	v_exp_f32_e32 v56, v56
	v_exp_f32_e32 v57, v57
	v_pk_add_f32 v[30:31], v[30:31], s[98:99]
	v_pk_add_f32 v[32:33], v[32:33], s[98:99]
	v_pk_add_f32 v[54:55], v[54:55], s[98:99]
	v_pk_add_f32 v[56:57], v[56:57], s[98:99]
	v_rcp_f32_e32 v30, v30
	v_rcp_f32_e32 v31, v31
	v_rcp_f32_e32 v32, v32
	v_rcp_f32_e32 v33, v33
	v_rcp_f32_e32 v54, v54
	v_rcp_f32_e32 v55, v55
	v_rcp_f32_e32 v56, v56
	v_rcp_f32_e32 v57, v57
	v_pk_mul_f32 v[34:35], v[34:35], v[66:67]
	v_pk_mul_f32 v[36:37], v[36:37], v[68:69]
	v_pk_mul_f32 v[82:83], v[82:83], v[98:99]
	v_pk_mul_f32 v[84:85], v[84:85], v[100:101]
	v_pk_mul_f32 v[34:35], v[34:35], v[30:31]
	v_pk_mul_f32 v[36:37], v[36:37], v[32:33]
	v_pk_mul_f32 v[82:83], v[82:83], v[54:55]
	v_pk_mul_f32 v[84:85], v[84:85], v[56:57]
	s_add_u32 s52, s88, 0x9000000
	s_addc_u32 s53, s89, 0
	v_cvt_pk_bf16_f32 v134, v62, v63
	v_cvt_pk_bf16_f32 v135, v64, v65
	v_cvt_pk_bf16_f32 v136, v42, v43
	v_cvt_pk_bf16_f32 v137, v44, v45
	global_store_dwordx4 v244, v[134:137], s[52:53]
	v_add_u32_e32 v244, 0x1600, v244
	v_cvt_pk_bf16_f32 v74, v50, v51
	v_cvt_pk_bf16_f32 v75, v52, v53
	v_cvt_pk_bf16_f32 v76, v38, v39
	v_cvt_pk_bf16_f32 v77, v40, v41
	global_store_dwordx4 v244, v[74:77], s[52:53]
	v_add_u32_e32 v244, 0x1600, v244
	v_cvt_pk_bf16_f32 v134, v46, v47
	v_cvt_pk_bf16_f32 v135, v48, v49
	v_cvt_pk_bf16_f32 v136, v34, v35
	v_cvt_pk_bf16_f32 v137, v36, v37
	global_store_dwordx4 v244, v[134:137], s[52:53]
	v_add_u32_e32 v244, 0x1600, v244
	v_cvt_pk_bf16_f32 v74, v142, v143
	v_cvt_pk_bf16_f32 v75, v144, v145
	v_cvt_pk_bf16_f32 v76, v82, v83
	v_cvt_pk_bf16_f32 v77, v84, v85
	global_store_dwordx4 v244, v[74:77], s[52:53]
	v_add_u32_e32 v244, 0xffffbe00, v244
	s_waitcnt lgkmcnt(0)
	ds_read_b128 v[146:149], v226 offset:0
	ds_read_b128 v[150:153], v226 offset:1024
	ds_read_b128 v[154:157], v226 offset:2048
	ds_read_b128 v[158:161], v226 offset:3072
	ds_read_b128 v[162:165], v227 offset:4096
	ds_read_b128 v[166:169], v227 offset:5120
	v_mov_b32_dpp v118, v102 row_shr:1 row_mask:0xf bank_mask:0xf
	v_mov_b32_dpp v122, v126 row_shr:1 row_mask:0xf bank_mask:0xf
	v_mov_b32_dpp v119, v103 row_shr:1 row_mask:0xf bank_mask:0xf
	v_mov_b32_dpp v123, v127 row_shr:1 row_mask:0xf bank_mask:0xf
	v_mov_b32_dpp v120, v104 row_shr:1 row_mask:0xf bank_mask:0xf
	v_mov_b32_dpp v124, v128 row_shr:1 row_mask:0xf bank_mask:0xf
	v_mov_b32_dpp v121, v105 row_shr:1 row_mask:0xf bank_mask:0xf
	v_mov_b32_dpp v125, v129 row_shr:1 row_mask:0xf bank_mask:0xf
	v_pk_fma_f32 v[126:127], v[204:205], v[126:127], v[208:209]
	v_pk_fma_f32 v[128:129], v[206:207], v[128:129], v[210:211]
	v_pk_fma_f32 v[126:127], v[200:201], v[102:103], v[126:127]
	v_pk_fma_f32 v[128:129], v[202:203], v[104:105], v[128:129]
	v_pk_fma_f32 v[102:103], v[204:205], v[102:103], v[208:209]
	v_pk_fma_f32 v[104:105], v[206:207], v[104:105], v[210:211]
	v_pk_fma_f32 v[126:127], v[196:197], v[106:107], v[126:127]
	v_pk_fma_f32 v[128:129], v[198:199], v[108:109], v[128:129]
	v_pk_fma_f32 v[102:103], v[200:201], v[106:107], v[102:103]
	v_pk_fma_f32 v[104:105], v[202:203], v[108:109], v[104:105]
	v_pk_fma_f32 v[106:107], v[204:205], v[106:107], v[208:209]
	v_pk_fma_f32 v[108:109], v[206:207], v[108:109], v[210:211]
	v_pk_fma_f32 v[102:103], v[196:197], v[110:111], v[102:103]
	v_pk_fma_f32 v[104:105], v[198:199], v[112:113], v[104:105]
	v_pk_fma_f32 v[106:107], v[200:201], v[110:111], v[106:107]
	v_pk_fma_f32 v[108:109], v[202:203], v[112:113], v[108:109]
	v_pk_fma_f32 v[110:111], v[204:205], v[110:111], v[208:209]
	v_pk_fma_f32 v[112:113], v[206:207], v[112:113], v[210:211]
	v_pk_fma_f32 v[106:107], v[196:197], v[122:123], v[106:107]
	v_pk_fma_f32 v[108:109], v[198:199], v[124:125], v[108:109]
	v_pk_fma_f32 v[110:111], v[200:201], v[122:123], v[110:111]
	v_pk_fma_f32 v[112:113], v[202:203], v[124:125], v[112:113]
	v_pk_fma_f32 v[110:111], v[196:197], v[118:119], v[110:111]
	v_pk_fma_f32 v[112:113], v[198:199], v[120:121], v[112:113]
	s_waitcnt lgkmcnt(0)
	ds_read_b128 v[196:199], v226 offset:528
	ds_read_b128 v[200:203], v226 offset:1552
	ds_read_b128 v[204:207], v226 offset:2576
	ds_read_b128 v[208:211], v226 offset:3600
	ds_read_b128 v[118:121], v227 offset:4624
	ds_read_b128 v[122:125], v227 offset:5648
	v_mov_b32_dpp v162, v86 row_shr:1 row_mask:0xf bank_mask:0xf
	v_mov_b32_dpp v166, v114 row_shr:1 row_mask:0xf bank_mask:0xf
	v_mov_b32_dpp v163, v87 row_shr:1 row_mask:0xf bank_mask:0xf
	v_mov_b32_dpp v167, v115 row_shr:1 row_mask:0xf bank_mask:0xf
	v_mov_b32_dpp v164, v88 row_shr:1 row_mask:0xf bank_mask:0xf
	v_mov_b32_dpp v168, v116 row_shr:1 row_mask:0xf bank_mask:0xf
	v_mov_b32_dpp v165, v89 row_shr:1 row_mask:0xf bank_mask:0xf
	v_mov_b32_dpp v169, v117 row_shr:1 row_mask:0xf bank_mask:0xf
	v_pk_fma_f32 v[114:115], v[154:155], v[114:115], v[158:159]
	v_pk_fma_f32 v[116:117], v[156:157], v[116:117], v[160:161]
	v_pk_fma_f32 v[114:115], v[150:151], v[86:87], v[114:115]
	v_pk_fma_f32 v[116:117], v[152:153], v[88:89], v[116:117]
	v_pk_fma_f32 v[86:87], v[154:155], v[86:87], v[158:159]
	v_pk_fma_f32 v[88:89], v[156:157], v[88:89], v[160:161]
	v_pk_fma_f32 v[114:115], v[146:147], v[90:91], v[114:115]
	v_pk_fma_f32 v[116:117], v[148:149], v[92:93], v[116:117]
	v_pk_fma_f32 v[86:87], v[150:151], v[90:91], v[86:87]
	v_pk_fma_f32 v[88:89], v[152:153], v[92:93], v[88:89]
	v_pk_fma_f32 v[90:91], v[154:155], v[90:91], v[158:159]
	v_pk_fma_f32 v[92:93], v[156:157], v[92:93], v[160:161]
	v_pk_fma_f32 v[86:87], v[146:147], v[94:95], v[86:87]
	v_pk_fma_f32 v[88:89], v[148:149], v[96:97], v[88:89]
	v_pk_fma_f32 v[90:91], v[150:151], v[94:95], v[90:91]
	v_pk_fma_f32 v[92:93], v[152:153], v[96:97], v[92:93]
	v_pk_fma_f32 v[94:95], v[154:155], v[94:95], v[158:159]
	v_pk_fma_f32 v[96:97], v[156:157], v[96:97], v[160:161]
	v_pk_fma_f32 v[90:91], v[146:147], v[166:167], v[90:91]
	v_pk_fma_f32 v[92:93], v[148:149], v[168:169], v[92:93]
	v_pk_fma_f32 v[94:95], v[150:151], v[166:167], v[94:95]
	v_pk_fma_f32 v[96:97], v[152:153], v[168:169], v[96:97]
	v_pk_fma_f32 v[94:95], v[146:147], v[162:163], v[94:95]
	v_pk_fma_f32 v[96:97], v[148:149], v[164:165], v[96:97]
	v_pk_mul_f32 v[30:31], v[94:95], s[100:101]
	v_pk_mul_f32 v[32:33], v[96:97], s[100:101]
	v_pk_mul_f32 v[54:55], v[90:91], s[100:101]
	v_pk_mul_f32 v[56:57], v[92:93], s[100:101]
	v_exp_f32_e32 v30, v30
	v_exp_f32_e32 v31, v31
	v_exp_f32_e32 v32, v32
	v_exp_f32_e32 v33, v33
	v_exp_f32_e32 v54, v54
	v_exp_f32_e32 v55, v55
	v_exp_f32_e32 v56, v56
	v_exp_f32_e32 v57, v57
	v_pk_add_f32 v[30:31], v[30:31], s[98:99]
	v_pk_add_f32 v[32:33], v[32:33], s[98:99]
	v_pk_add_f32 v[54:55], v[54:55], s[98:99]
	v_pk_add_f32 v[56:57], v[56:57], s[98:99]
	v_rcp_f32_e32 v30, v30
	v_rcp_f32_e32 v31, v31
	v_rcp_f32_e32 v32, v32
	v_rcp_f32_e32 v33, v33
	v_rcp_f32_e32 v54, v54
	v_rcp_f32_e32 v55, v55
	v_rcp_f32_e32 v56, v56
	v_rcp_f32_e32 v57, v57
	v_pk_mul_f32 v[94:95], v[94:95], v[110:111]
	v_pk_mul_f32 v[96:97], v[96:97], v[112:113]
	v_pk_mul_f32 v[90:91], v[90:91], v[106:107]
	v_pk_mul_f32 v[92:93], v[92:93], v[108:109]
	v_pk_mul_f32 v[94:95], v[94:95], v[30:31]
	v_pk_mul_f32 v[96:97], v[96:97], v[32:33]
	v_pk_mul_f32 v[90:91], v[90:91], v[54:55]
	v_pk_mul_f32 v[92:93], v[92:93], v[56:57]
	v_pk_mul_f32 v[30:31], v[86:87], s[100:101]
	v_pk_mul_f32 v[32:33], v[88:89], s[100:101]
	v_pk_mul_f32 v[54:55], v[114:115], s[100:101]
	v_pk_mul_f32 v[56:57], v[116:117], s[100:101]
	v_exp_f32_e32 v30, v30
	v_exp_f32_e32 v31, v31
	v_exp_f32_e32 v32, v32
	v_exp_f32_e32 v33, v33
	v_exp_f32_e32 v54, v54
	v_exp_f32_e32 v55, v55
	v_exp_f32_e32 v56, v56
	v_exp_f32_e32 v57, v57
	v_pk_add_f32 v[30:31], v[30:31], s[98:99]
	v_pk_add_f32 v[32:33], v[32:33], s[98:99]
	v_pk_add_f32 v[54:55], v[54:55], s[98:99]
	v_pk_add_f32 v[56:57], v[56:57], s[98:99]
	v_rcp_f32_e32 v30, v30
	v_rcp_f32_e32 v31, v31
	v_rcp_f32_e32 v32, v32
	v_rcp_f32_e32 v33, v33
	v_rcp_f32_e32 v54, v54
	v_rcp_f32_e32 v55, v55
	v_rcp_f32_e32 v56, v56
	v_rcp_f32_e32 v57, v57
	v_pk_mul_f32 v[86:87], v[86:87], v[102:103]
	v_pk_mul_f32 v[88:89], v[88:89], v[104:105]
	v_pk_mul_f32 v[114:115], v[114:115], v[126:127]
	v_pk_mul_f32 v[116:117], v[116:117], v[128:129]
	v_pk_mul_f32 v[86:87], v[86:87], v[30:31]
	v_pk_mul_f32 v[88:89], v[88:89], v[32:33]
	v_pk_mul_f32 v[114:115], v[114:115], v[54:55]
	v_pk_mul_f32 v[116:117], v[116:117], v[56:57]
	s_waitcnt lgkmcnt(0)
	ds_read_b128 v[146:149], v226 offset:16
	ds_read_b128 v[150:153], v226 offset:1040
	ds_read_b128 v[154:157], v226 offset:2064
	ds_read_b128 v[158:161], v226 offset:3088
	ds_read_b128 v[162:165], v227 offset:4112
	ds_read_b128 v[166:169], v227 offset:5136
	v_mov_b32_dpp v118, v14 row_shr:1 row_mask:0xf bank_mask:0xf
	v_mov_b32_dpp v122, v58 row_shr:1 row_mask:0xf bank_mask:0xf
	v_mov_b32_dpp v119, v15 row_shr:1 row_mask:0xf bank_mask:0xf
	v_mov_b32_dpp v123, v59 row_shr:1 row_mask:0xf bank_mask:0xf
	v_mov_b32_dpp v120, v16 row_shr:1 row_mask:0xf bank_mask:0xf
	v_mov_b32_dpp v124, v60 row_shr:1 row_mask:0xf bank_mask:0xf
	v_mov_b32_dpp v121, v17 row_shr:1 row_mask:0xf bank_mask:0xf
	v_mov_b32_dpp v125, v61 row_shr:1 row_mask:0xf bank_mask:0xf
	v_pk_fma_f32 v[58:59], v[204:205], v[58:59], v[208:209]
	v_pk_fma_f32 v[60:61], v[206:207], v[60:61], v[210:211]
	v_pk_fma_f32 v[58:59], v[200:201], v[14:15], v[58:59]
	v_pk_fma_f32 v[60:61], v[202:203], v[16:17], v[60:61]
	v_pk_fma_f32 v[14:15], v[204:205], v[14:15], v[208:209]
	v_pk_fma_f32 v[16:17], v[206:207], v[16:17], v[210:211]
	v_pk_fma_f32 v[58:59], v[196:197], v[18:19], v[58:59]
	v_pk_fma_f32 v[60:61], v[198:199], v[20:21], v[60:61]
	v_pk_fma_f32 v[14:15], v[200:201], v[18:19], v[14:15]
	v_pk_fma_f32 v[16:17], v[202:203], v[20:21], v[16:17]
	v_pk_fma_f32 v[18:19], v[204:205], v[18:19], v[208:209]
	v_pk_fma_f32 v[20:21], v[206:207], v[20:21], v[210:211]
	v_pk_fma_f32 v[14:15], v[196:197], v[22:23], v[14:15]
	v_pk_fma_f32 v[16:17], v[198:199], v[24:25], v[16:17]
	v_pk_fma_f32 v[18:19], v[200:201], v[22:23], v[18:19]
	v_pk_fma_f32 v[20:21], v[202:203], v[24:25], v[20:21]
	v_pk_fma_f32 v[22:23], v[204:205], v[22:23], v[208:209]
	v_pk_fma_f32 v[24:25], v[206:207], v[24:25], v[210:211]
	v_pk_fma_f32 v[18:19], v[196:197], v[122:123], v[18:19]
	v_pk_fma_f32 v[20:21], v[198:199], v[124:125], v[20:21]
	v_pk_fma_f32 v[22:23], v[200:201], v[122:123], v[22:23]
	v_pk_fma_f32 v[24:25], v[202:203], v[124:125], v[24:25]
	v_pk_fma_f32 v[22:23], v[196:197], v[118:119], v[22:23]
	v_pk_fma_f32 v[24:25], v[198:199], v[120:121], v[24:25]
	s_waitcnt lgkmcnt(0)
	v_mov_b32_dpp v162, v2 row_shr:1 row_mask:0xf bank_mask:0xf
	v_mov_b32_dpp v166, v26 row_shr:1 row_mask:0xf bank_mask:0xf
	v_mov_b32_dpp v163, v3 row_shr:1 row_mask:0xf bank_mask:0xf
	v_mov_b32_dpp v167, v27 row_shr:1 row_mask:0xf bank_mask:0xf
	v_mov_b32_dpp v164, v4 row_shr:1 row_mask:0xf bank_mask:0xf
	v_mov_b32_dpp v168, v28 row_shr:1 row_mask:0xf bank_mask:0xf
	v_mov_b32_dpp v165, v5 row_shr:1 row_mask:0xf bank_mask:0xf
	v_mov_b32_dpp v169, v29 row_shr:1 row_mask:0xf bank_mask:0xf
	v_pk_fma_f32 v[26:27], v[154:155], v[26:27], v[158:159]
	v_pk_fma_f32 v[28:29], v[156:157], v[28:29], v[160:161]
	v_pk_fma_f32 v[26:27], v[150:151], v[2:3], v[26:27]
	v_pk_fma_f32 v[28:29], v[152:153], v[4:5], v[28:29]
	v_pk_fma_f32 v[2:3], v[154:155], v[2:3], v[158:159]
	v_pk_fma_f32 v[4:5], v[156:157], v[4:5], v[160:161]
	v_pk_fma_f32 v[26:27], v[146:147], v[6:7], v[26:27]
	v_pk_fma_f32 v[28:29], v[148:149], v[8:9], v[28:29]
	v_pk_fma_f32 v[2:3], v[150:151], v[6:7], v[2:3]
	v_pk_fma_f32 v[4:5], v[152:153], v[8:9], v[4:5]
	v_pk_fma_f32 v[6:7], v[154:155], v[6:7], v[158:159]
	v_pk_fma_f32 v[8:9], v[156:157], v[8:9], v[160:161]
	v_pk_fma_f32 v[2:3], v[146:147], v[10:11], v[2:3]
	v_pk_fma_f32 v[4:5], v[148:149], v[12:13], v[4:5]
	v_pk_fma_f32 v[6:7], v[150:151], v[10:11], v[6:7]
	v_pk_fma_f32 v[8:9], v[152:153], v[12:13], v[8:9]
	v_pk_fma_f32 v[10:11], v[154:155], v[10:11], v[158:159]
	v_pk_fma_f32 v[12:13], v[156:157], v[12:13], v[160:161]
	v_pk_fma_f32 v[6:7], v[146:147], v[166:167], v[6:7]
	v_pk_fma_f32 v[8:9], v[148:149], v[168:169], v[8:9]
	v_pk_fma_f32 v[10:11], v[150:151], v[166:167], v[10:11]
	v_pk_fma_f32 v[12:13], v[152:153], v[168:169], v[12:13]
	v_pk_fma_f32 v[10:11], v[146:147], v[162:163], v[10:11]
	v_pk_fma_f32 v[12:13], v[148:149], v[164:165], v[12:13]
	v_pk_mul_f32 v[30:31], v[10:11], s[100:101]
	v_pk_mul_f32 v[32:33], v[12:13], s[100:101]
	v_pk_mul_f32 v[54:55], v[6:7], s[100:101]
	v_pk_mul_f32 v[56:57], v[8:9], s[100:101]
	v_exp_f32_e32 v30, v30
	v_exp_f32_e32 v31, v31
	v_exp_f32_e32 v32, v32
	v_exp_f32_e32 v33, v33
	v_exp_f32_e32 v54, v54
	v_exp_f32_e32 v55, v55
	v_exp_f32_e32 v56, v56
	v_exp_f32_e32 v57, v57
	v_pk_add_f32 v[30:31], v[30:31], s[98:99]
	v_pk_add_f32 v[32:33], v[32:33], s[98:99]
	v_pk_add_f32 v[54:55], v[54:55], s[98:99]
	v_pk_add_f32 v[56:57], v[56:57], s[98:99]
	v_rcp_f32_e32 v30, v30
	v_rcp_f32_e32 v31, v31
	v_rcp_f32_e32 v32, v32
	v_rcp_f32_e32 v33, v33
	v_rcp_f32_e32 v54, v54
	v_rcp_f32_e32 v55, v55
	v_rcp_f32_e32 v56, v56
	v_rcp_f32_e32 v57, v57
	v_pk_mul_f32 v[10:11], v[10:11], v[22:23]
	v_pk_mul_f32 v[12:13], v[12:13], v[24:25]
	v_pk_mul_f32 v[6:7], v[6:7], v[18:19]
	v_pk_mul_f32 v[8:9], v[8:9], v[20:21]
	v_pk_mul_f32 v[10:11], v[10:11], v[30:31]
	v_pk_mul_f32 v[12:13], v[12:13], v[32:33]
	v_pk_mul_f32 v[6:7], v[6:7], v[54:55]
	v_pk_mul_f32 v[8:9], v[8:9], v[56:57]
	v_pk_mul_f32 v[30:31], v[2:3], s[100:101]
	v_pk_mul_f32 v[32:33], v[4:5], s[100:101]
	v_pk_mul_f32 v[54:55], v[26:27], s[100:101]
	v_pk_mul_f32 v[56:57], v[28:29], s[100:101]
	v_exp_f32_e32 v30, v30
	v_exp_f32_e32 v31, v31
	v_exp_f32_e32 v32, v32
	v_exp_f32_e32 v33, v33
	v_exp_f32_e32 v54, v54
	v_exp_f32_e32 v55, v55
	v_exp_f32_e32 v56, v56
	v_exp_f32_e32 v57, v57
	v_pk_add_f32 v[30:31], v[30:31], s[98:99]
	v_pk_add_f32 v[32:33], v[32:33], s[98:99]
	v_pk_add_f32 v[54:55], v[54:55], s[98:99]
	v_pk_add_f32 v[56:57], v[56:57], s[98:99]
	v_rcp_f32_e32 v30, v30
	v_rcp_f32_e32 v31, v31
	v_rcp_f32_e32 v32, v32
	v_rcp_f32_e32 v33, v33
	v_rcp_f32_e32 v54, v54
	v_rcp_f32_e32 v55, v55
	v_rcp_f32_e32 v56, v56
	v_rcp_f32_e32 v57, v57
	v_pk_mul_f32 v[2:3], v[2:3], v[14:15]
	v_pk_mul_f32 v[4:5], v[4:5], v[16:17]
	v_pk_mul_f32 v[26:27], v[26:27], v[58:59]
	v_pk_mul_f32 v[28:29], v[28:29], v[60:61]
	v_pk_mul_f32 v[2:3], v[2:3], v[30:31]
	v_pk_mul_f32 v[4:5], v[4:5], v[32:33]
	v_pk_mul_f32 v[26:27], v[26:27], v[54:55]
	v_pk_mul_f32 v[28:29], v[28:29], v[56:57]
	v_add_u32_e32 v244, 0xb0000, v244
	v_cvt_pk_bf16_f32 v110, v94, v95
	v_cvt_pk_bf16_f32 v111, v96, v97
	v_cvt_pk_bf16_f32 v112, v10, v11
	v_cvt_pk_bf16_f32 v113, v12, v13
	global_store_dwordx4 v244, v[110:113], s[52:53]
	v_add_u32_e32 v244, 0x1600, v244
	v_cvt_pk_bf16_f32 v22, v90, v91
	v_cvt_pk_bf16_f32 v23, v92, v93
	v_cvt_pk_bf16_f32 v24, v6, v7
	v_cvt_pk_bf16_f32 v25, v8, v9
	global_store_dwordx4 v244, v[22:25], s[52:53]
	v_add_u32_e32 v244, 0x1600, v244
	v_cvt_pk_bf16_f32 v110, v86, v87
	v_cvt_pk_bf16_f32 v111, v88, v89
	v_cvt_pk_bf16_f32 v112, v2, v3
	v_cvt_pk_bf16_f32 v113, v4, v5
	global_store_dwordx4 v244, v[110:113], s[52:53]
	v_add_u32_e32 v244, 0x1600, v244
	v_cvt_pk_bf16_f32 v22, v114, v115
	v_cvt_pk_bf16_f32 v23, v116, v117
	v_cvt_pk_bf16_f32 v24, v26, v27
	v_cvt_pk_bf16_f32 v25, v28, v29
	global_store_dwordx4 v244, v[22:25], s[52:53]
	s_cmp_lg_u32 s54, 1
	s_cselect_b64 s[8:9], -1, 0
	s_andn2_b64 vcc, exec, s[4:5]
	s_mov_b64 s[4:5], -1
	s_cbranch_vccnz .LBB0_1313
	s_andn2_b64 vcc, exec, s[20:21]
	s_mov_b32 s43, s44
	s_mov_b64 s[30:31], s[16:17]
	s_mov_b64 s[4:5], s[40:41]
	s_cbranch_vccnz .LBB0_1350
	s_ashr_i32 s4, s44, 5
	s_mul_hi_i32 s5, s4, 0x5800
	s_mulk_i32 s4, 0x5800
	s_add_u32 s30, s3, s4
	s_addc_u32 s31, s6, s5
	s_mov_b32 s43, s42
	s_mov_b64 s[4:5], s[14:15]
